# speedup vs baseline: 1.0013x; 1.0013x over previous
.LBB0_471:
	s_and_b32 s0, s13, 0x2000
	s_add_i32 s16, s0, 16
	s_add_i32 s16, s16, 0x20000
	ds_read_b128 v[16:19], v237
	ds_read_b128 v[206:209], v238
	ds_read_b128 v[210:213], v239
	ds_read_b128 v[214:217], v240
	ds_read_b128 v[218:221], v241
	ds_read_b128 v[222:225], v242
	ds_read_b128 v[226:229], v243
	ds_read_b128 v[230:233], v244
	s_waitcnt lgkmcnt(7)
	v_mfma_f32_32x32x16_bf16 v[0:15], v[96:99], v[16:19], 0
	v_max_f32_e32 v183, 0, v32
	v_fma_f32 v183, v92, v183, 0
	v_max_f32_e32 v236, 0, v34
	v_max_f32_e32 v205, 0, v48
	v_fmac_f32_e32 v183, v94, v236
	v_mfma_f32_32x32x16_bf16 v[16:31], v[128:131], v[16:19], 0
	v_max_f32_e32 v236, v50, v50
	v_fma_f32 v205, v88, v205, 0
	v_max_f32_e32 v234, 0, v33
	v_fma_f32 v234, v93, v234, 0
	v_max_f32_e32 v235, 0, v49
	s_waitcnt lgkmcnt(6)
	v_mfma_f32_32x32x16_bf16 v[0:15], v[100:103], v[206:209], v[0:15]
	v_fma_f32 v235, v89, v235, 0
	v_mfma_f32_32x32x16_bf16 v[16:31], v[132:135], v[206:209], v[16:31]
	v_max_f32_e32 v206, 0, v236
	v_fmac_f32_e32 v205, v90, v206
	v_max_f32_e32 v206, 0, v35
	v_fmac_f32_e32 v234, v95, v206
	v_max_f32_e32 v206, 0, v51
	v_fmac_f32_e32 v235, v91, v206
	v_max_f32_e32 v206, 0, v36
	v_fmac_f32_e32 v183, v84, v206
	v_max_f32_e32 v206, 0, v52
	v_fmac_f32_e32 v205, v80, v206
	v_max_f32_e32 v206, 0, v37
	v_fmac_f32_e32 v234, v85, v206
	v_max_f32_e32 v206, 0, v53
	s_waitcnt lgkmcnt(5)
	v_mfma_f32_32x32x16_bf16 v[0:15], v[104:107], v[210:213], v[0:15]
	v_fmac_f32_e32 v235, v81, v206
	v_max_f32_e32 v206, 0, v38
	v_fmac_f32_e32 v183, v86, v206
	v_max_f32_e32 v206, 0, v54
	v_fmac_f32_e32 v205, v82, v206
	v_mfma_f32_32x32x16_bf16 v[16:31], v[136:139], v[210:213], v[16:31]
	v_max_f32_e32 v206, 0, v39
	v_fmac_f32_e32 v234, v87, v206
	v_max_f32_e32 v206, 0, v55
	v_fmac_f32_e32 v235, v83, v206
	s_waitcnt lgkmcnt(4)
	v_mfma_f32_32x32x16_bf16 v[0:15], v[108:111], v[214:217], v[0:15]
	v_max_f32_e32 v206, 0, v40
	v_fmac_f32_e32 v183, v72, v206
	v_max_f32_e32 v206, 0, v56
	s_waitcnt vmcnt(1)
	v_fmac_f32_e32 v205, v76, v206
	v_max_f32_e32 v206, 0, v41
	v_mfma_f32_32x32x16_bf16 v[16:31], v[140:143], v[214:217], v[16:31]
	v_fmac_f32_e32 v234, v73, v206
	v_max_f32_e32 v206, 0, v57
	v_fmac_f32_e32 v235, v77, v206
	v_max_f32_e32 v206, 0, v42
	v_fmac_f32_e32 v183, v74, v206
	s_waitcnt lgkmcnt(3)
	v_mfma_f32_32x32x16_bf16 v[0:15], v[112:115], v[218:221], v[0:15]
	v_max_f32_e32 v206, 0, v58
	v_fmac_f32_e32 v205, v78, v206
	v_max_f32_e32 v206, 0, v43
	v_fmac_f32_e32 v234, v75, v206
	v_mfma_f32_32x32x16_bf16 v[16:31], v[144:147], v[218:221], v[16:31]
	v_max_f32_e32 v206, 0, v59
	v_fmac_f32_e32 v235, v79, v206
	v_max_f32_e32 v206, 0, v44
	v_fmac_f32_e32 v183, v64, v206
	v_max_f32_e32 v206, 0, v60
	s_waitcnt lgkmcnt(2)
	v_mfma_f32_32x32x16_bf16 v[0:15], v[116:119], v[222:225], v[0:15]
	s_waitcnt vmcnt(0)
	v_fmac_f32_e32 v205, v68, v206
	v_max_f32_e32 v206, 0, v45
	v_fmac_f32_e32 v234, v65, v206
	v_max_f32_e32 v206, 0, v61
	v_fmac_f32_e32 v235, v69, v206
	v_mfma_f32_32x32x16_bf16 v[16:31], v[148:151], v[222:225], v[16:31]
	v_max_f32_e32 v206, 0, v46
	v_fmac_f32_e32 v183, v66, v206
	v_max_f32_e32 v206, 0, v62
	v_fmac_f32_e32 v205, v70, v206
	s_waitcnt lgkmcnt(1)
	v_mfma_f32_32x32x16_bf16 v[0:15], v[120:123], v[226:229], v[0:15]
	v_max_f32_e32 v206, 0, v47
	v_fmac_f32_e32 v234, v67, v206
	v_max_f32_e32 v206, 0, v63
	v_fmac_f32_e32 v235, v71, v206
	v_add_f32_e32 v183, v183, v205
	v_add_f32_e32 v205, v234, v235
	v_mfma_f32_32x32x16_bf16 v[16:31], v[152:155], v[226:229], v[16:31]
	v_add_f32_e32 v183, v183, v205
	v_mov_b32_e32 v205, v183
	s_waitcnt lgkmcnt(0)
	v_mfma_f32_32x32x16_bf16 v[0:15], v[124:127], v[230:233], v[0:15]
	v_mfma_f32_32x32x16_bf16 v[16:31], v[156:159], v[230:233], v[16:31]
	v_permlane32_swap_b32_e32 v183, v205
	s_and_saveexec_b64 s[0:1], s[4:5]
	s_cbranch_execz .LBB0_473
	v_add_f32_e32 v183, v183, v205
	ds_write_b32 v204, v183

.LBB0_477:
	ds_read_b128 v[48:51], v245
	ds_read_b128 v[206:209], v246
	ds_read_b128 v[210:213], v247
	ds_read_b128 v[214:217], v248
	ds_read_b128 v[218:221], v249
	ds_read_b128 v[222:225], v251
	ds_read_b128 v[226:229], v252
	ds_read_b128 v[230:233], v253
	s_waitcnt lgkmcnt(7)
	v_mfma_f32_32x32x16_bf16 v[32:47], v[96:99], v[48:51], 0
	v_max_f32_e32 v183, 0, v0
	v_fma_f32 v183, v92, v183, 0
	v_max_f32_e32 v236, 0, v2
	v_max_f32_e32 v205, 0, v16
	v_fmac_f32_e32 v183, v94, v236
	v_mfma_f32_32x32x16_bf16 v[48:63], v[128:131], v[48:51], 0
	v_max_f32_e32 v236, v18, v18
	v_fma_f32 v205, v88, v205, 0
	v_max_f32_e32 v234, 0, v1
	v_fma_f32 v234, v93, v234, 0
	v_max_f32_e32 v235, 0, v17
	s_waitcnt lgkmcnt(6)
	v_mfma_f32_32x32x16_bf16 v[32:47], v[100:103], v[206:209], v[32:47]
	v_fma_f32 v235, v89, v235, 0
	v_mfma_f32_32x32x16_bf16 v[48:63], v[132:135], v[206:209], v[48:63]
	v_max_f32_e32 v206, 0, v236
	v_fmac_f32_e32 v205, v90, v206
	v_max_f32_e32 v206, 0, v3
	v_fmac_f32_e32 v234, v95, v206
	v_max_f32_e32 v206, 0, v19
	v_fmac_f32_e32 v235, v91, v206
	v_max_f32_e32 v206, 0, v4
	v_fmac_f32_e32 v183, v84, v206
	v_max_f32_e32 v206, 0, v20
	v_fmac_f32_e32 v205, v80, v206
	v_max_f32_e32 v206, 0, v5
	v_fmac_f32_e32 v234, v85, v206
	v_max_f32_e32 v206, 0, v21
	s_waitcnt lgkmcnt(5)
	v_mfma_f32_32x32x16_bf16 v[32:47], v[104:107], v[210:213], v[32:47]
	v_fmac_f32_e32 v235, v81, v206
	v_max_f32_e32 v206, 0, v6
	v_fmac_f32_e32 v183, v86, v206
	v_max_f32_e32 v206, 0, v22
	v_fmac_f32_e32 v205, v82, v206
	v_mfma_f32_32x32x16_bf16 v[48:63], v[136:139], v[210:213], v[48:63]
	v_max_f32_e32 v206, 0, v7
	v_fmac_f32_e32 v234, v87, v206
	v_max_f32_e32 v206, 0, v23
	v_fmac_f32_e32 v235, v83, v206
	s_waitcnt lgkmcnt(4)
	v_mfma_f32_32x32x16_bf16 v[32:47], v[108:111], v[214:217], v[32:47]
	v_max_f32_e32 v206, 0, v8
	v_fmac_f32_e32 v183, v72, v206
	v_max_f32_e32 v206, 0, v24
	v_fmac_f32_e32 v205, v76, v206
	v_max_f32_e32 v206, 0, v9
	v_mfma_f32_32x32x16_bf16 v[48:63], v[140:143], v[214:217], v[48:63]
	v_fmac_f32_e32 v234, v73, v206
	v_max_f32_e32 v206, 0, v25
	v_fmac_f32_e32 v235, v77, v206
	v_max_f32_e32 v206, 0, v10
	v_fmac_f32_e32 v183, v74, v206
	s_waitcnt lgkmcnt(3)
	v_mfma_f32_32x32x16_bf16 v[32:47], v[112:115], v[218:221], v[32:47]
	v_max_f32_e32 v206, 0, v26
	v_fmac_f32_e32 v205, v78, v206
	v_max_f32_e32 v206, 0, v11
	v_fmac_f32_e32 v234, v75, v206
	v_mfma_f32_32x32x16_bf16 v[48:63], v[144:147], v[218:221], v[48:63]
	v_max_f32_e32 v206, 0, v27
	v_fmac_f32_e32 v235, v79, v206
	v_max_f32_e32 v206, 0, v12
	v_fmac_f32_e32 v183, v64, v206
	v_max_f32_e32 v206, 0, v28
	s_waitcnt lgkmcnt(2)
	v_mfma_f32_32x32x16_bf16 v[32:47], v[116:119], v[222:225], v[32:47]
	v_fmac_f32_e32 v205, v68, v206
	v_max_f32_e32 v206, 0, v13
	v_fmac_f32_e32 v234, v65, v206
	v_max_f32_e32 v206, 0, v29
	v_fmac_f32_e32 v235, v69, v206
	v_mfma_f32_32x32x16_bf16 v[48:63], v[148:151], v[222:225], v[48:63]
	v_max_f32_e32 v206, 0, v14
	v_fmac_f32_e32 v183, v66, v206
	v_max_f32_e32 v206, 0, v30
	v_fmac_f32_e32 v205, v70, v206
	s_waitcnt lgkmcnt(1)
	v_mfma_f32_32x32x16_bf16 v[32:47], v[120:123], v[226:229], v[32:47]
	v_max_f32_e32 v206, 0, v15
	v_fmac_f32_e32 v234, v67, v206
	v_max_f32_e32 v206, 0, v31
	v_fmac_f32_e32 v235, v71, v206
	v_add_f32_e32 v183, v183, v205
	v_add_f32_e32 v205, v234, v235
	v_mfma_f32_32x32x16_bf16 v[48:63], v[152:155], v[226:229], v[48:63]
	v_add_f32_e32 v183, v183, v205
	v_mov_b32_e32 v205, v183
	s_waitcnt lgkmcnt(0)
	v_mfma_f32_32x32x16_bf16 v[32:47], v[124:127], v[230:233], v[32:47]
	v_mfma_f32_32x32x16_bf16 v[48:63], v[156:159], v[230:233], v[48:63]
	v_permlane32_swap_b32_e32 v183, v205
	s_and_saveexec_b64 s[0:1], s[4:5]
	s_cbranch_execz .LBB0_479
	v_add_f32_e32 v183, v183, v205
	ds_write_b32 v204, v183 offset:128
